# input-projection GEMM epilogue: tiles whose 256 columns all go to one destination buffer (7 of 10 column tiles) take the plain bf16 store path instead of per-lane predicated 3-way scatter
# speedup vs baseline: 1.0103x; 1.0003x over previous
; #define BIGEPI_LOOP(F, CHK) \
;     _Pragma("unroll") for (int ai = 0; ai < 2; ++ai) _Pragma("unroll") for (int m = 0; m < 4; ++m) { \
;       _Pragma("unroll") for (int bj = 0; bj < 2; ++bj) { \
;         const int c = col0 + bj * 128; \
;         if (!(CHK) || c < N) F(row0 + ai * 128 + m * 16, c, acc[ai][bj][m][0], acc[ai][bj][m][1]); } \
;       __builtin_amdgcn_sched_barrier(0); }
;   DI void f_z8(int m, int n, f32x4 v0, f32x4 v1) const {
;     u16* dst;
;     if (n < 448) dst = o0 + (size_t)m * 832 + n;
;     else if (n < 1984) dst = o1 + (size_t)m * 1536 + (n - 448);
;     else dst = o0 + (size_t)m * 832 + (n - 1984 + 448);
;     st8(dst, v0, v1);
;   }
;   DI void operator()(const f32x4 (&acc)[2][2][4][2], const pg8::Unit& u, int wr, int wc, int fr, int fq) const {
;     ...
;     if (mode == 0) { if (u.pn == (DINP / 256 - 1)) { BIGEPI_LOOP(f_z8, true) } else { BIGEPI_LOOP(f_z8, false) } }
.LBB0_752:
	s_andn2_b64 vcc, exec, s[0:1]
	s_cbranch_vccnz .LBB0_737
	s_cmp_lg_u32 s77, 1
	s_mov_b64 s[0:1], -1
	s_cbranch_scc0 .LBB0_1031
	s_cmp_eq_u32 s97, 0
	s_cbranch_scc1 .Lm0_A
	s_cmp_eq_u32 s97, 8
	s_cbranch_scc1 .Lm0_C
	s_cmp_lt_u32 s97, 2
	s_cbranch_scc1 .Lm0_orig
	s_cmp_gt_u32 s97, 6
	s_cbranch_scc1 .Lm0_orig
	s_mov_b64 s[44:45], 0x600
	v_add_u32_e32 v178, 0xf9fffe40, v178
	s_branch .Lm1_body
.Lm0_C:
	s_mov_b64 s[44:45], 0x340
	v_add_u32_e32 v178, 0xfffffa00, v178
	s_branch .Lm1_body
.Lm0_A:
	s_mov_b64 s[44:45], 0x340
	s_branch .Lm1_body
.Lm0_orig:
	v_mad_i64_i32 v[130:131], s[0:1], v176, s19, 0
	v_mad_i64_i32 v[132:133], s[0:1], v176, s50, 0
	s_movk_i32 s0, 0x1bf
	s_cmp_eq_u32 s97, 9
	s_mov_b64 s[22:23], -1
	v_cmp_lt_i32_e64 s[0:1], s0, v178
	s_cbranch_scc1 .LBB0_876
	s_and_saveexec_b64 s[22:23], s[0:1]
	s_xor_b64 s[22:23], exec, s[22:23]
	s_cbranch_execz .LBB0_760
	s_cmpk_gt_u32 s75, 0x7bf
	v_mov_b32_e32 v179, v0
	s_mov_b64 s[38:39], -1
	s_cbranch_scc0 .LBB0_758
	v_lshl_add_u64 v[134:135], s[46:47], 0, v[130:131]
	s_movk_i32 s38, 0xf400
	v_lshl_add_u64 v[134:135], v[178:179], 1, v[134:135]
	s_mov_b32 s39, -1
	v_lshl_add_u64 v[134:135], v[134:135], 0, s[38:39]
	s_mov_b64 s[38:39], 0

; DI unsigned pack2(float a, float b) { f32x2_t v = {a, b}; bf16x2_t r = __builtin_convertvector(v, bf16x2_t); return __builtin_bit_cast(unsigned, r); }
; #define BIGEPI_LOOP(F, CHK) \
;     _Pragma("unroll") for (int ai = 0; ai < 2; ++ai) _Pragma("unroll") for (int m = 0; m < 4; ++m) { \
;       _Pragma("unroll") for (int bj = 0; bj < 2; ++bj) { \
;         const int c = col0 + bj * 128; \
;         if (!(CHK) || c < N) F(row0 + ai * 128 + m * 16, c, acc[ai][bj][m][0], acc[ai][bj][m][1]); } \
;       __builtin_amdgcn_sched_barrier(0); }
;   DI static void st8(u16* dst, f32x4 v0, f32x4 v1) {
;     uint4 o; o.x = pack2(v0[0], v0[1]); o.y = pack2(v0[2], v0[3]); o.z = pack2(v1[0], v1[1]); o.w = pack2(v1[2], v1[3]);
;     *(uint4*)dst = o;
;   }
;   DI void f_z8(int m, int n, f32x4 v0, f32x4 v1) const {
;     u16* dst;
;     if (n < 448) dst = o0 + (size_t)m * 832 + n;
;     else if (n < 1984) dst = o1 + (size_t)m * 1536 + (n - 448);
;     else dst = o0 + (size_t)m * 832 + (n - 1984 + 448);
;     st8(dst, v0, v1);
;   }
;   DI void f_store8(int m, int n, f32x4 v0, f32x4 v1) const { st8(o0 + (size_t)m * ld + n, v0, v1); }
;   DI void operator()(const f32x4 (&acc)[2][2][4][2], const pg8::Unit& u, int wr, int wc, int fr, int fq) const {
;     ...
;     if (mode == 0) { if (u.pn == (DINP / 256 - 1)) { BIGEPI_LOOP(f_z8, true) } else { BIGEPI_LOOP(f_z8, false) } }
.Lm1_body:
	v_ashrrev_i32_e32 v130, 31, v176
	v_mul_lo_u32 v132, s45, v176
	v_mul_lo_u32 v134, s44, v130
	v_mad_u64_u32 v[130:131], s[0:1], s44, v176, 0
	v_add3_u32 v131, v131, v134, v132
	v_ashrrev_i32_e32 v179, 31, v178
	v_lshl_add_u64 v[130:131], v[130:131], 1, s[46:47]
	v_lshlrev_b64 v[132:133], 1, v[178:179]
	v_lshl_add_u64 v[130:131], v[130:131], 0, v[132:133]
	v_cvt_pk_bf16_f32 v126, v126, v127
	v_cvt_pk_bf16_f32 v127, v128, v129
	v_cvt_pk_bf16_f32 v128, v122, v123
	v_cvt_pk_bf16_f32 v129, v124, v125
	v_cvt_pk_bf16_f32 v110, v110, v111
	v_cvt_pk_bf16_f32 v111, v112, v113
	v_cvt_pk_bf16_f32 v112, v106, v107
	v_cvt_pk_bf16_f32 v113, v108, v109
	global_store_dwordx4 v[130:131], v[126:129], off
	global_store_dwordx4 v[130:131], v[110:113], off offset:256
	v_or_b32_e32 v106, 16, v176
	v_mul_lo_u32 v108, s45, v106
	v_mad_u64_u32 v[106:107], s[0:1], s44, v106, 0
	v_add3_u32 v107, v107, v134, v108
	v_lshl_add_u64 v[106:107], v[106:107], 1, s[46:47]
	v_lshl_add_u64 v[110:111], v[106:107], 0, v[132:133]
	v_cvt_pk_bf16_f32 v106, v118, v119
	v_cvt_pk_bf16_f32 v107, v120, v121
	v_cvt_pk_bf16_f32 v108, v114, v115
	v_cvt_pk_bf16_f32 v109, v116, v117
	v_cvt_pk_bf16_f32 v94, v94, v95
	v_cvt_pk_bf16_f32 v95, v96, v97
	v_cvt_pk_bf16_f32 v96, v90, v91
	v_cvt_pk_bf16_f32 v97, v92, v93
	global_store_dwordx4 v[110:111], v[106:109], off
	global_store_dwordx4 v[110:111], v[94:97], off offset:256
	v_or_b32_e32 v90, 32, v176
	v_mul_lo_u32 v92, s45, v90
	v_mad_u64_u32 v[90:91], s[0:1], s44, v90, 0
	v_add3_u32 v91, v91, v134, v92
	v_lshl_add_u64 v[90:91], v[90:91], 1, s[46:47]
	v_lshl_add_u64 v[94:95], v[90:91], 0, v[132:133]
	v_cvt_pk_bf16_f32 v90, v102, v103
	v_cvt_pk_bf16_f32 v91, v104, v105
	v_cvt_pk_bf16_f32 v92, v98, v99
	v_cvt_pk_bf16_f32 v93, v100, v101
	v_cvt_pk_bf16_f32 v78, v78, v79
	v_cvt_pk_bf16_f32 v79, v80, v81
	v_cvt_pk_bf16_f32 v80, v74, v75
	v_cvt_pk_bf16_f32 v81, v76, v77
	global_store_dwordx4 v[94:95], v[90:93], off
	global_store_dwordx4 v[94:95], v[78:81], off offset:256
	v_or_b32_e32 v74, 48, v176
	v_mul_lo_u32 v76, s45, v74
	v_mad_u64_u32 v[74:75], s[0:1], s44, v74, 0
	v_add3_u32 v75, v75, v134, v76
	v_lshl_add_u64 v[74:75], v[74:75], 1, s[46:47]
	v_lshl_add_u64 v[78:79], v[74:75], 0, v[132:133]
	v_cvt_pk_bf16_f32 v74, v86, v87
	v_cvt_pk_bf16_f32 v75, v88, v89
	v_cvt_pk_bf16_f32 v76, v82, v83
	v_cvt_pk_bf16_f32 v77, v84, v85
	v_cvt_pk_bf16_f32 v70, v70, v71
	v_cvt_pk_bf16_f32 v71, v72, v73
	v_cvt_pk_bf16_f32 v72, v66, v67
	v_cvt_pk_bf16_f32 v73, v68, v69
	global_store_dwordx4 v[78:79], v[74:77], off
	global_store_dwordx4 v[78:79], v[70:73], off offset:256
	v_add_u32_e32 v66, 0x80, v176
	v_ashrrev_i32_e32 v67, 31, v66
	v_mul_lo_u32 v68, s44, v67
	v_mul_lo_u32 v69, s45, v66
	v_mad_u64_u32 v[66:67], s[0:1], s44, v66, 0
	v_add3_u32 v67, v67, v68, v69
	v_lshl_add_u64 v[66:67], v[66:67], 1, s[46:47]
	v_lshl_add_u64 v[66:67], v[66:67], 0, v[132:133]
	v_cvt_pk_bf16_f32 v62, v62, v63
	v_cvt_pk_bf16_f32 v63, v64, v65
	v_cvt_pk_bf16_f32 v64, v58, v59
	v_cvt_pk_bf16_f32 v65, v60, v61
	v_cvt_pk_bf16_f32 v46, v46, v47
	v_cvt_pk_bf16_f32 v47, v48, v49
	v_cvt_pk_bf16_f32 v48, v42, v43
	v_cvt_pk_bf16_f32 v49, v44, v45
	global_store_dwordx4 v[66:67], v[62:65], off
	global_store_dwordx4 v[66:67], v[46:49], off offset:256
	v_add_u32_e32 v42, 0x90, v176
	v_ashrrev_i32_e32 v43, 31, v42
	v_mul_lo_u32 v44, s44, v43
	v_mul_lo_u32 v45, s45, v42
	v_mad_u64_u32 v[42:43], s[0:1], s44, v42, 0
	v_add3_u32 v43, v43, v44, v45
	v_lshl_add_u64 v[42:43], v[42:43], 1, s[46:47]
	v_lshl_add_u64 v[46:47], v[42:43], 0, v[132:133]
	v_cvt_pk_bf16_f32 v42, v54, v55
	v_cvt_pk_bf16_f32 v43, v56, v57
	v_cvt_pk_bf16_f32 v44, v50, v51
	v_cvt_pk_bf16_f32 v45, v52, v53
	v_cvt_pk_bf16_f32 v30, v30, v31
	v_cvt_pk_bf16_f32 v31, v32, v33
	v_cvt_pk_bf16_f32 v32, v26, v27
	v_cvt_pk_bf16_f32 v33, v28, v29
	global_store_dwordx4 v[46:47], v[42:45], off
	global_store_dwordx4 v[46:47], v[30:33], off offset:256
	v_add_u32_e32 v26, 0xa0, v176
	v_ashrrev_i32_e32 v27, 31, v26
	v_mul_lo_u32 v28, s44, v27
	v_mul_lo_u32 v29, s45, v26
	v_mad_u64_u32 v[26:27], s[0:1], s44, v26, 0
	v_add3_u32 v27, v27, v28, v29
	v_lshl_add_u64 v[26:27], v[26:27], 1, s[46:47]
	v_lshl_add_u64 v[30:31], v[26:27], 0, v[132:133]
	v_cvt_pk_bf16_f32 v26, v38, v39
	v_cvt_pk_bf16_f32 v27, v40, v41
	v_cvt_pk_bf16_f32 v28, v34, v35
	v_cvt_pk_bf16_f32 v29, v36, v37
	v_cvt_pk_bf16_f32 v14, v14, v15
	v_cvt_pk_bf16_f32 v15, v16, v17
	v_cvt_pk_bf16_f32 v16, v10, v11
	v_cvt_pk_bf16_f32 v17, v12, v13
	global_store_dwordx4 v[30:31], v[26:29], off
	global_store_dwordx4 v[30:31], v[14:17], off offset:256
	v_add_u32_e32 v10, 0xb0, v176
	v_ashrrev_i32_e32 v11, 31, v10
	v_mul_lo_u32 v12, s44, v11
	v_mul_lo_u32 v13, s45, v10
	v_mad_u64_u32 v[10:11], s[0:1], s44, v10, 0
	v_add3_u32 v11, v11, v12, v13
	v_lshl_add_u64 v[10:11], v[10:11], 1, s[46:47]
	v_lshl_add_u64 v[14:15], v[10:11], 0, v[132:133]
	v_cvt_pk_bf16_f32 v10, v22, v23
	v_cvt_pk_bf16_f32 v11, v24, v25
	v_cvt_pk_bf16_f32 v12, v18, v19
	v_cvt_pk_bf16_f32 v13, v20, v21
	v_cvt_pk_bf16_f32 v6, v6, v7
	v_cvt_pk_bf16_f32 v7, v8, v9
	v_cvt_pk_bf16_f32 v8, v2, v3
	v_cvt_pk_bf16_f32 v9, v4, v5
	global_store_dwordx4 v[14:15], v[10:13], off
	global_store_dwordx4 v[14:15], v[6:9], off offset:256
	s_branch .LBB0_737
